# S5 pass C: x prefetch of the next sub-block no longer drained by the sample-only vmcnt(0) waits (counted wait at the consumer)
# baseline (speedup 1.0000x reference)
.LBB0_272:
	ds_read_b128 v[106:109], v158
	ds_read_b128 v[110:113], v158 offset:16
	s_add_u32 s16, s16, 0x10000
	s_addc_u32 s17, s17, 0
	s_add_i32 s42, s42, 1
	s_waitcnt lgkmcnt(1)
	v_cvt_pk_bf16_f32 v168, v106, v107
	v_cvt_pk_bf16_f32 v169, v108, v109
	v_lshlrev_b32_e32 v172, 16, v168
	v_and_b32_e32 v173, 0xffff0000, v168
	s_waitcnt lgkmcnt(0)
	v_cvt_pk_bf16_f32 v170, v110, v111
	v_cvt_pk_bf16_f32 v171, v112, v113
	v_pk_add_f32 v[106:107], v[106:107], v[172:173] neg_lo:[0,1] neg_hi:[0,1]
	v_lshlrev_b32_e32 v172, 16, v169
	v_and_b32_e32 v173, 0xffff0000, v169
	v_pk_add_f32 v[108:109], v[108:109], v[172:173] neg_lo:[0,1] neg_hi:[0,1]
	v_cvt_pk_bf16_f32 v106, v106, v107
	v_cvt_pk_bf16_f32 v107, v108, v109
	v_lshlrev_b32_e32 v108, 16, v170
	v_and_b32_e32 v109, 0xffff0000, v170
	v_pk_add_f32 v[108:109], v[110:111], v[108:109] neg_lo:[0,1] neg_hi:[0,1]
	v_lshlrev_b32_e32 v110, 16, v171
	v_and_b32_e32 v111, 0xffff0000, v171
	v_pk_add_f32 v[172:173], v[112:113], v[110:111] neg_lo:[0,1] neg_hi:[0,1]
	v_cvt_pk_bf16_f32 v108, v108, v109
	v_mfma_f32_16x16x32_bf16 v[110:113], v[168:171], v[26:29], 0
	v_cvt_pk_bf16_f32 v109, v172, v173
	ds_read_b128 v[172:175], v158 offset:128
	ds_read_b128 v[176:179], v158 offset:144
	v_lshl_add_u64 v[142:143], v[142:143], 0, s[10:11]
	v_mfma_f32_16x16x32_bf16 v[110:113], v[168:171], v[30:33], v[110:113]
	v_lshl_add_u64 v[144:145], v[144:145], 0, s[10:11]
	s_waitcnt lgkmcnt(1)
	v_cvt_pk_bf16_f32 v168, v172, v173
	v_cvt_pk_bf16_f32 v169, v174, v175
	v_lshlrev_b32_e32 v180, 16, v168
	v_and_b32_e32 v181, 0xffff0000, v168
	v_pk_add_f32 v[172:173], v[172:173], v[180:181] neg_lo:[0,1] neg_hi:[0,1]
	v_lshlrev_b32_e32 v180, 16, v169
	v_and_b32_e32 v181, 0xffff0000, v169
	s_waitcnt lgkmcnt(0)
	v_cvt_pk_bf16_f32 v170, v176, v177
	v_pk_add_f32 v[174:175], v[174:175], v[180:181] neg_lo:[0,1] neg_hi:[0,1]
	v_cvt_pk_bf16_f32 v171, v178, v179
	v_cvt_pk_bf16_f32 v172, v172, v173
	v_cvt_pk_bf16_f32 v173, v174, v175
	v_lshlrev_b32_e32 v174, 16, v170
	v_and_b32_e32 v175, 0xffff0000, v170
	v_pk_add_f32 v[174:175], v[176:177], v[174:175] neg_lo:[0,1] neg_hi:[0,1]
	v_lshlrev_b32_e32 v176, 16, v171
	v_and_b32_e32 v177, 0xffff0000, v171
	v_pk_add_f32 v[176:177], v[178:179], v[176:177] neg_lo:[0,1] neg_hi:[0,1]
	v_cvt_pk_bf16_f32 v174, v174, v175
	v_cvt_pk_bf16_f32 v175, v176, v177
	v_mfma_f32_16x16x32_bf16 v[106:109], v[106:109], v[26:29], 0
	s_cmp_eq_u32 s22, s16
	v_mfma_f32_16x16x32_bf16 v[110:113], v[168:171], v[18:21], v[110:113]
	v_mfma_f32_16x16x32_bf16 v[106:109], v[172:175], v[18:21], v[106:109]
	ds_read_b128 v[172:175], v158 offset:256
	ds_read_b128 v[176:179], v158 offset:272
	v_mfma_f32_16x16x32_bf16 v[110:113], v[168:171], v[22:25], v[110:113]
	s_waitcnt lgkmcnt(1)
	v_cvt_pk_bf16_f32 v168, v172, v173
	v_cvt_pk_bf16_f32 v169, v174, v175
	v_lshlrev_b32_e32 v180, 16, v168
	v_and_b32_e32 v181, 0xffff0000, v168
	v_pk_add_f32 v[172:173], v[172:173], v[180:181] neg_lo:[0,1] neg_hi:[0,1]
	v_lshlrev_b32_e32 v180, 16, v169
	v_and_b32_e32 v181, 0xffff0000, v169
	s_waitcnt lgkmcnt(0)
	v_cvt_pk_bf16_f32 v170, v176, v177
	v_pk_add_f32 v[174:175], v[174:175], v[180:181] neg_lo:[0,1] neg_hi:[0,1]
	v_cvt_pk_bf16_f32 v171, v178, v179
	v_cvt_pk_bf16_f32 v172, v172, v173
	v_cvt_pk_bf16_f32 v173, v174, v175
	v_lshlrev_b32_e32 v174, 16, v170
	v_and_b32_e32 v175, 0xffff0000, v170
	v_pk_add_f32 v[174:175], v[176:177], v[174:175] neg_lo:[0,1] neg_hi:[0,1]
	v_lshlrev_b32_e32 v176, 16, v171
	v_and_b32_e32 v177, 0xffff0000, v171
	v_pk_add_f32 v[176:177], v[178:179], v[176:177] neg_lo:[0,1] neg_hi:[0,1]
	v_cvt_pk_bf16_f32 v174, v174, v175
	v_cvt_pk_bf16_f32 v175, v176, v177
	v_mfma_f32_16x16x32_bf16 v[110:113], v[168:171], v[10:13], v[110:113]
	s_nop 0
	v_mfma_f32_16x16x32_bf16 v[106:109], v[172:175], v[10:13], v[106:109]
	ds_read_b128 v[172:175], v158 offset:384
	ds_read_b128 v[176:179], v158 offset:400
	v_mfma_f32_16x16x32_bf16 v[110:113], v[168:171], v[14:17], v[110:113]
	s_waitcnt lgkmcnt(1)
	v_cvt_pk_bf16_f32 v168, v172, v173
	v_cvt_pk_bf16_f32 v169, v174, v175
	v_lshlrev_b32_e32 v180, 16, v168
	v_and_b32_e32 v181, 0xffff0000, v168
	v_pk_add_f32 v[172:173], v[172:173], v[180:181] neg_lo:[0,1] neg_hi:[0,1]
	v_lshlrev_b32_e32 v180, 16, v169
	v_and_b32_e32 v181, 0xffff0000, v169
	s_waitcnt lgkmcnt(0)
	v_cvt_pk_bf16_f32 v170, v176, v177
	v_cvt_pk_bf16_f32 v171, v178, v179
	v_pk_add_f32 v[174:175], v[174:175], v[180:181] neg_lo:[0,1] neg_hi:[0,1]
	v_cvt_pk_bf16_f32 v172, v172, v173
	v_cvt_pk_bf16_f32 v173, v174, v175
	v_lshlrev_b32_e32 v174, 16, v170
	v_and_b32_e32 v175, 0xffff0000, v170
	v_pk_add_f32 v[174:175], v[176:177], v[174:175] neg_lo:[0,1] neg_hi:[0,1]
	v_lshlrev_b32_e32 v176, 16, v171
	v_and_b32_e32 v177, 0xffff0000, v171
	v_pk_add_f32 v[176:177], v[178:179], v[176:177] neg_lo:[0,1] neg_hi:[0,1]
	v_cvt_pk_bf16_f32 v174, v174, v175
	v_cvt_pk_bf16_f32 v175, v176, v177
	v_mfma_f32_16x16x32_bf16 v[110:113], v[168:171], v[2:5], v[110:113]
	s_nop 0
	v_mfma_f32_16x16x32_bf16 v[106:109], v[172:175], v[2:5], v[106:109]
	v_mfma_f32_16x16x32_bf16 v[110:113], v[168:171], v[6:9], v[110:113]
	s_nop 7
	v_pk_add_f32 v[106:107], v[106:107], v[110:111]
	v_pk_add_f32 v[108:109], v[108:109], v[112:113]
	v_fma_f32 v106, v160, v163, v106
	v_mul_f32_e32 v110, v106, v106
	v_fmamk_f32 v110, v110, 0x3dd2d3e8, v159
	v_mul_f32_e64 v110, v106, -v110
	v_fmac_f32_e32 v107, v160, v161
	v_exp_f32_e32 v111, v110
	v_mul_f32_e32 v112, v107, v107
	v_fmamk_f32 v112, v112, 0x3dd2d3e8, v159
	v_mul_f32_e64 v112, v107, -v112
	v_exp_f32_e32 v112, v112
	v_add_f32_e32 v111, 1.0, v111
	v_rcp_f32_e32 v111, v111
	v_add_u32_e32 v110, -3, v140
	v_add_f32_e32 v112, 1.0, v112
	v_rcp_f32_e32 v112, v112
	v_mul_f32_e32 v106, v106, v111
	v_ashrrev_i32_e32 v111, 31, v110
	v_lshlrev_b64 v[110:111], 12, v[110:111]
	v_cvt_pk_bf16_f32 v106, v106, s0
	v_lshl_add_u64 v[110:111], v[146:147], 0, v[110:111]
	v_fma_f32 v108, v160, v141, v108
	global_store_short v[110:111], v106, off
	v_mul_f32_e32 v106, v107, v112
	v_mul_f32_e32 v107, v108, v108
	v_fmamk_f32 v107, v107, 0x3dd2d3e8, v159
	v_mul_f32_e64 v107, v108, -v107
	v_exp_f32_e32 v110, v107
	v_cvt_pk_bf16_f32 v111, v106, s0
	v_add_u32_e32 v106, -2, v140
	v_ashrrev_i32_e32 v107, 31, v106
	v_add_f32_e32 v110, 1.0, v110
	v_lshlrev_b64 v[106:107], 12, v[106:107]
	v_rcp_f32_e32 v110, v110
	v_lshl_add_u64 v[106:107], v[146:147], 0, v[106:107]
	v_fmac_f32_e32 v109, v160, v139
	global_store_short v[106:107], v111, off
	v_mul_f32_e32 v107, v109, v109
	v_fmamk_f32 v107, v107, 0x3dd2d3e8, v159
	v_mul_f32_e64 v107, v109, -v107
	v_mul_f32_e32 v106, v108, v110
	v_exp_f32_e32 v108, v107
	v_cvt_pk_bf16_f32 v110, v106, s0
	v_add_u32_e32 v106, -1, v140
	v_ashrrev_i32_e32 v107, 31, v106
	v_add_f32_e32 v108, 1.0, v108
	v_rcp_f32_e32 v108, v108
	v_lshlrev_b64 v[106:107], 12, v[106:107]
	v_lshl_add_u64 v[106:107], v[146:147], 0, v[106:107]
	global_store_short v[106:107], v110, off
	v_mul_f32_e32 v106, v109, v108
	v_ashrrev_i32_e32 v141, 31, v140
	v_cvt_pk_bf16_f32 v108, v106, s0
	v_lshlrev_b64 v[106:107], 12, v[140:141]
	v_lshl_add_u64 v[106:107], v[146:147], 0, v[106:107]
	global_store_short v[106:107], v108, off
	s_waitcnt vmcnt(4)
	v_mov_b64_e32 v[112:113], v[104:105]
	v_mov_b64_e32 v[108:109], v[100:101]
	v_add_u32_e32 v140, 16, v140
	v_mov_b64_e32 v[110:111], v[102:103]
	v_mov_b64_e32 v[106:107], v[98:99]
	v_mov_b32_e32 v163, v162
	v_mov_b32_e32 v161, v164
	v_mov_b32_e32 v141, v165
	v_mov_b32_e32 v139, v166
	s_cbranch_scc1 .LBB0_281

.LBB0_275:
	v_cvt_pk_bf16_f32 v167, v110, v111
	v_lshlrev_b32_e32 v168, 16, v167
	v_and_b32_e32 v169, 0xffff0000, v167
	v_cvt_pk_bf16_f32 v170, v112, v113
	v_pk_add_f32 v[110:111], v[110:111], v[168:169] neg_lo:[0,1] neg_hi:[0,1]
	v_cvt_pk_bf16_f32 v171, v106, v107
	v_cvt_pk_bf16_f32 v168, v110, v111
	v_lshlrev_b32_e32 v110, 16, v170
	v_and_b32_e32 v111, 0xffff0000, v170
	v_pk_add_f32 v[110:111], v[112:113], v[110:111] neg_lo:[0,1] neg_hi:[0,1]
	v_cvt_pk_bf16_f32 v172, v108, v109
	v_cvt_pk_bf16_f32 v112, v110, v111
	v_lshlrev_b32_e32 v110, 16, v171
	v_and_b32_e32 v111, 0xffff0000, v171
	v_pk_add_f32 v[106:107], v[106:107], v[110:111] neg_lo:[0,1] neg_hi:[0,1]
	s_andn2_b64 vcc, exec, s[12:13]
	v_cvt_pk_bf16_f32 v110, v106, v107
	v_lshlrev_b32_e32 v106, 16, v172
	v_and_b32_e32 v107, 0xffff0000, v172
	v_pk_add_f32 v[106:107], v[108:109], v[106:107] neg_lo:[0,1] neg_hi:[0,1]
	v_cndmask_b32_e64 v108, v110, v171, s[4:5]
	v_cvt_pk_bf16_f32 v106, v106, v107
	v_cndmask_b32_e64 v109, v106, v172, s[4:5]
	v_cndmask_b32_e64 v107, v112, v170, s[4:5]
	v_cndmask_b32_e64 v106, v168, v167, s[4:5]
	s_nop 1
	v_mfma_f32_16x16x32_bf16 v[110:113], v[106:109], v[86:89], 0
	v_mfma_f32_16x16x32_bf16 v[168:171], v[106:109], v[70:73], 0
	v_mfma_f32_16x16x32_bf16 v[172:175], v[106:109], v[54:57], 0
	v_mfma_f32_16x16x32_bf16 v[110:113], v[106:109], v[94:97], v[110:113]
	s_nop 7
	ds_write_b32 v156, v110
	ds_write_b32 v156, v111 offset:528
	v_mfma_f32_16x16x32_bf16 v[168:171], v[106:109], v[78:81], v[168:171]
	ds_write_b32 v156, v112 offset:1056
	ds_write_b32 v157, v113
	s_nop 5
	ds_write_b32 v156, v168 offset:64
	ds_write_b32 v156, v169 offset:592
	ds_write_b32 v156, v170 offset:1120
	ds_write_b32 v157, v171 offset:64
	v_mfma_f32_16x16x32_bf16 v[176:179], v[106:109], v[38:41], 0
	v_mfma_f32_16x16x32_bf16 v[180:183], v[106:109], v[82:85], 0
	v_mfma_f32_16x16x32_bf16 v[168:171], v[106:109], v[62:65], v[172:175]
	s_nop 7
	ds_write_b32 v156, v168 offset:128
	ds_write_b32 v156, v169 offset:656
	ds_write_b32 v156, v170 offset:1184
	v_mfma_f32_16x16x32_bf16 v[172:175], v[106:109], v[46:49], v[176:179]
	ds_write_b32 v157, v171 offset:128
	s_nop 6
	ds_write_b32 v156, v172 offset:192
	ds_write_b32 v156, v173 offset:720
	v_mfma_f32_16x16x32_bf16 v[184:187], v[106:109], v[66:69], 0
	v_mfma_f32_16x16x32_bf16 v[188:191], v[106:109], v[50:53], 0
	v_mfma_f32_16x16x32_bf16 v[168:171], v[106:109], v[90:93], v[180:183]
	ds_write_b32 v156, v174 offset:1248
	ds_write_b32 v157, v175 offset:192
	s_nop 5
	ds_write_b32 v156, v168 offset:256
	ds_write_b32 v156, v169 offset:784
	ds_write_b32 v156, v170 offset:1312
	ds_write_b32 v157, v171 offset:256
	v_mfma_f32_16x16x32_bf16 v[110:113], v[106:109], v[34:37], 0
	v_mfma_f32_16x16x32_bf16 v[172:175], v[106:109], v[74:77], v[184:187]
	s_nop 7
	ds_write_b32 v156, v172 offset:320
	ds_write_b32 v156, v173 offset:848
	ds_write_b32 v156, v174 offset:1376
	v_mfma_f32_16x16x32_bf16 v[168:171], v[106:109], v[58:61], v[188:191]
	v_mfma_f32_16x16x32_bf16 v[106:109], v[106:109], v[42:45], v[110:113]
	ds_write_b32 v157, v175 offset:320
	s_nop 5
	ds_write_b32 v156, v168 offset:384
	ds_write_b32 v156, v169 offset:912
	ds_write_b32 v156, v170 offset:1440
	ds_write_b32 v157, v171 offset:384
	ds_write_b32 v156, v106 offset:448
	ds_write_b32 v156, v107 offset:976
	ds_write_b32 v156, v108 offset:1504
	ds_write_b32 v157, v109 offset:448
	v_cndmask_b32_e64 v106, 0, 1, s[12:13]
	v_cmp_ne_u32_e64 s[6:7], 1, v106
	v_lshl_add_u64 v[108:109], v[150:151], 0, s[16:17]
	v_lshl_add_u64 v[110:111], v[148:149], 0, s[16:17]
	s_cbranch_vccnz .LBB0_277
	global_load_dword v155, v[110:111], off
	global_load_dword v154, v[108:109], off
	s_waitcnt vmcnt(0)
.LBB0_277:
	ds_read2st64_b32 v[106:107], v115 offset1:1
	v_pk_mul_f32 v[112:113], v[154:155], v[116:117]
	v_add_u32_e32 v167, 32, v115
	v_pk_fma_f32 v[168:169], v[154:155], v[118:119], v[112:113] op_sel:[0,0,1] op_sel_hi:[1,1,0]
	v_pk_fma_f32 v[112:113], v[154:155], v[118:119], v[112:113] op_sel:[0,0,1] op_sel_hi:[1,1,0] neg_lo:[0,0,1] neg_hi:[0,0,1]
	ds_read2st64_b32 v[154:155], v167 offset0:4 offset1:5
	v_mov_b32_e32 v169, v113
	s_waitcnt lgkmcnt(1)
	v_mov_b32_e32 v112, v107
	v_mov_b32_e32 v113, v106
	v_pk_add_f32 v[106:107], v[168:169], v[112:113]
	ds_read2_b32 v[112:113], v115 offset0:132 offset1:196
	v_pk_mul_f32 v[172:173], v[106:107], v[116:117]
	ds_write2st64_b32 v115, v107, v106 offset1:1
	v_pk_fma_f32 v[174:175], v[106:107], v[118:119], v[172:173] op_sel:[0,0,1] op_sel_hi:[1,1,0]
	v_pk_fma_f32 v[106:107], v[106:107], v[118:119], v[172:173] op_sel:[0,0,1] op_sel_hi:[1,1,0] neg_lo:[0,0,1] neg_hi:[0,0,1]
	v_add_u32_e32 v176, 48, v115
	v_mov_b32_e32 v175, v107
	s_waitcnt lgkmcnt(1)
	v_mov_b32_e32 v106, v113
	v_mov_b32_e32 v107, v112
	v_pk_add_f32 v[106:107], v[174:175], v[106:107]
	ds_read2st64_b32 v[168:169], v176 offset0:6 offset1:7
	v_pk_mul_f32 v[112:113], v[106:107], v[116:117]
	ds_write2_b32 v115, v107, v106 offset0:132 offset1:196
	v_pk_fma_f32 v[172:173], v[106:107], v[118:119], v[112:113] op_sel:[0,0,1] op_sel_hi:[1,1,0]
	v_pk_fma_f32 v[106:107], v[106:107], v[118:119], v[112:113] op_sel:[0,0,1] op_sel_hi:[1,1,0] neg_lo:[0,0,1] neg_hi:[0,0,1]
	v_add_u32_e32 v177, 64, v115
	v_mov_b32_e32 v173, v107
	v_mov_b32_e32 v106, v155
	v_mov_b32_e32 v107, v154
	v_pk_add_f32 v[106:107], v[172:173], v[106:107]
	ds_write2st64_b32 v167, v107, v106 offset0:4 offset1:5
	v_pk_mul_f32 v[112:113], v[106:107], v[116:117]
	ds_read2st64_b32 v[170:171], v177 offset0:8 offset1:9
	v_pk_fma_f32 v[154:155], v[106:107], v[118:119], v[112:113] op_sel:[0,0,1] op_sel_hi:[1,1,0]
	v_pk_fma_f32 v[106:107], v[106:107], v[118:119], v[112:113] op_sel:[0,0,1] op_sel_hi:[1,1,0] neg_lo:[0,0,1] neg_hi:[0,0,1]
	v_add_u32_e32 v167, 0x50, v115
	v_mov_b32_e32 v155, v107
	s_waitcnt lgkmcnt(3)
	v_mov_b32_e32 v106, v169
	v_mov_b32_e32 v107, v168
	v_pk_add_f32 v[106:107], v[154:155], v[106:107]
	ds_write2st64_b32 v176, v107, v106 offset0:6 offset1:7
	v_pk_mul_f32 v[112:113], v[106:107], v[116:117]
	s_waitcnt lgkmcnt(1)
	v_mov_b32_e32 v172, v171
	v_pk_fma_f32 v[154:155], v[106:107], v[118:119], v[112:113] op_sel:[0,0,1] op_sel_hi:[1,1,0]
	v_pk_fma_f32 v[106:107], v[106:107], v[118:119], v[112:113] op_sel:[0,0,1] op_sel_hi:[1,1,0] neg_lo:[0,0,1] neg_hi:[0,0,1]
	v_mov_b32_e32 v173, v170
	v_mov_b32_e32 v155, v107
	ds_read2st64_b32 v[106:107], v167 offset0:10 offset1:11
	v_pk_add_f32 v[154:155], v[154:155], v[172:173]
	v_add_u32_e32 v174, 0x60, v115
	v_pk_mul_f32 v[170:171], v[154:155], v[116:117]
	ds_read2st64_b32 v[112:113], v174 offset0:12 offset1:13
	ds_write2st64_b32 v177, v155, v154 offset0:8 offset1:9
	v_pk_fma_f32 v[172:173], v[154:155], v[118:119], v[170:171] op_sel:[0,0,1] op_sel_hi:[1,1,0]
	v_pk_fma_f32 v[154:155], v[154:155], v[118:119], v[170:171] op_sel:[0,0,1] op_sel_hi:[1,1,0] neg_lo:[0,0,1] neg_hi:[0,0,1]
	v_add_u32_e32 v175, 0x70, v115
	v_mov_b32_e32 v173, v155
	s_waitcnt lgkmcnt(2)
	v_mov_b32_e32 v154, v107
	v_mov_b32_e32 v155, v106
	v_pk_add_f32 v[106:107], v[172:173], v[154:155]
	ds_read2st64_b32 v[168:169], v175 offset0:14 offset1:15
	v_pk_mul_f32 v[154:155], v[106:107], v[116:117]
	ds_write2st64_b32 v167, v107, v106 offset0:10 offset1:11
	v_pk_fma_f32 v[170:171], v[106:107], v[118:119], v[154:155] op_sel:[0,0,1] op_sel_hi:[1,1,0]
	v_pk_fma_f32 v[106:107], v[106:107], v[118:119], v[154:155] op_sel:[0,0,1] op_sel_hi:[1,1,0] neg_lo:[0,0,1] neg_hi:[0,0,1]
	s_and_b64 vcc, exec, s[6:7]
	v_mov_b32_e32 v171, v107
	s_waitcnt lgkmcnt(3)
	v_mov_b32_e32 v106, v113
	v_mov_b32_e32 v107, v112
	v_pk_add_f32 v[106:107], v[170:171], v[106:107]
	ds_write2st64_b32 v174, v107, v106 offset0:12 offset1:13
	v_pk_mul_f32 v[112:113], v[106:107], v[116:117]
	s_nop 0
	v_pk_fma_f32 v[154:155], v[106:107], v[118:119], v[112:113] op_sel:[0,0,1] op_sel_hi:[1,1,0]
	v_pk_fma_f32 v[106:107], v[106:107], v[118:119], v[112:113] op_sel:[0,0,1] op_sel_hi:[1,1,0] neg_lo:[0,0,1] neg_hi:[0,0,1]
	s_nop 0
	v_mov_b32_e32 v155, v107
	s_waitcnt lgkmcnt(2)
	v_mov_b32_e32 v106, v169
	v_mov_b32_e32 v107, v168
	v_pk_add_f32 v[112:113], v[154:155], v[106:107]
	v_lshl_add_u64 v[106:107], v[152:153], 0, s[16:17]
	ds_write2st64_b32 v175, v113, v112 offset0:14 offset1:15
	s_cbranch_vccnz .LBB0_279
	v_add_co_u32_e32 v154, vcc, 0x6810000, v106
	s_nop 1
	v_addc_co_u32_e32 v155, vcc, 0, v107, vcc
	global_store_dword v[154:155], v113, off
	v_add_co_u32_e32 v154, vcc, 0x6c10000, v106
	s_nop 1
	v_addc_co_u32_e32 v155, vcc, 0, v107, vcc
	v_add_co_u32_e32 v110, vcc, 0x8000, v110
	global_store_dword v[154:155], v112, off
	s_nop 0
	v_addc_co_u32_e32 v111, vcc, 0, v111, vcc
	v_add_co_u32_e32 v108, vcc, 0x8000, v108
	global_load_dword v113, v[110:111], off
	s_nop 0
	v_addc_co_u32_e32 v109, vcc, 0, v109, vcc
	global_load_dword v112, v[108:109], off
	s_waitcnt vmcnt(0)
.LBB0_279:
	v_add_u32_e32 v154, 0x80, v115
	ds_read2st64_b32 v[108:109], v154 offset0:16 offset1:17
	v_mul_f32_e32 v110, v112, v116
	v_mul_f32_e32 v155, v113, v116
	v_fma_f32 v110, v113, v118, -v110
	v_fmac_f32_e32 v155, v112, v118
	v_add_u32_e32 v112, 0x90, v115
	s_waitcnt lgkmcnt(0)
	v_add_f32_e32 v108, v108, v110
	ds_read2st64_b32 v[110:111], v112 offset0:18 offset1:19
	v_add_f32_e32 v109, v155, v109
	v_mul_f32_e32 v113, v109, v116
	v_fma_f32 v113, v108, v118, -v113
	ds_write2st64_b32 v154, v108, v109 offset0:16 offset1:17
	s_waitcnt lgkmcnt(1)
	v_add_f32_e32 v110, v110, v113
	v_mul_f32_e32 v113, v108, v116
	v_add_u32_e32 v154, 0xa0, v115
	v_fmac_f32_e32 v113, v109, v118
	ds_read2st64_b32 v[108:109], v154 offset0:20 offset1:21
	v_add_f32_e32 v111, v113, v111
	ds_write2st64_b32 v112, v110, v111 offset0:18 offset1:19
	v_mul_f32_e32 v112, v111, v116
	v_fma_f32 v112, v110, v118, -v112
	s_waitcnt lgkmcnt(1)
	v_add_f32_e32 v108, v108, v112
	v_mul_f32_e32 v112, v110, v116
	v_add_u32_e32 v113, 0xb0, v115
	v_fmac_f32_e32 v112, v111, v118
	ds_read2st64_b32 v[110:111], v113 offset0:22 offset1:23
	v_add_f32_e32 v109, v112, v109
	v_mul_f32_e32 v112, v109, v116
	ds_write2st64_b32 v154, v108, v109 offset0:20 offset1:21
	v_fma_f32 v112, v108, v118, -v112
	v_mul_f32_e32 v108, v108, v116
	v_fmac_f32_e32 v108, v109, v118
	v_add_u32_e32 v167, 0xc0, v115
	s_waitcnt lgkmcnt(1)
	v_add_f32_e32 v110, v110, v112
	v_add_f32_e32 v112, v108, v111
	ds_read2st64_b32 v[108:109], v167 offset0:24 offset1:25
	v_mul_f32_e32 v111, v112, v116
	ds_write2st64_b32 v113, v110, v112 offset0:22 offset1:23
	v_fma_f32 v111, v110, v118, -v111
	v_mul_f32_e32 v110, v110, v116
	v_add_u32_e32 v172, 0xd0, v115
	v_fmac_f32_e32 v110, v112, v118
	ds_read2st64_b32 v[112:113], v172 offset0:26 offset1:27
	s_waitcnt lgkmcnt(2)
	v_mov_b32_e32 v170, v109
	v_mov_b32_e32 v171, v108
	v_pk_add_f32 v[108:109], v[110:111], v[170:171]
	v_add_u32_e32 v173, 0xe0, v115
	v_pk_mul_f32 v[110:111], v[108:109], v[116:117]
	ds_read2st64_b32 v[154:155], v173 offset0:28 offset1:29
	ds_write2st64_b32 v167, v109, v108 offset0:24 offset1:25
	v_pk_fma_f32 v[170:171], v[108:109], v[118:119], v[110:111] op_sel:[0,0,1] op_sel_hi:[1,1,0]
	v_pk_fma_f32 v[108:109], v[108:109], v[118:119], v[110:111] op_sel:[0,0,1] op_sel_hi:[1,1,0] neg_lo:[0,0,1] neg_hi:[0,0,1]
	v_add_u32_e32 v174, 0xf0, v115
	v_mov_b32_e32 v171, v109
	s_waitcnt lgkmcnt(2)
	v_mov_b32_e32 v108, v113
	v_mov_b32_e32 v109, v112
	v_pk_add_f32 v[108:109], v[170:171], v[108:109]
	ds_read2st64_b32 v[168:169], v174 offset0:30 offset1:31
	v_pk_mul_f32 v[110:111], v[108:109], v[116:117]
	ds_write2st64_b32 v172, v109, v108 offset0:26 offset1:27
	v_pk_fma_f32 v[112:113], v[108:109], v[118:119], v[110:111] op_sel:[0,0,1] op_sel_hi:[1,1,0]
	v_pk_fma_f32 v[108:109], v[108:109], v[118:119], v[110:111] op_sel:[0,0,1] op_sel_hi:[1,1,0] neg_lo:[0,0,1] neg_hi:[0,0,1]
	s_and_b64 vcc, exec, s[6:7]
	v_mov_b32_e32 v113, v109
	s_waitcnt lgkmcnt(3)
	v_mov_b32_e32 v108, v155
	v_mov_b32_e32 v109, v154
	v_pk_add_f32 v[108:109], v[112:113], v[108:109]
	ds_write2st64_b32 v173, v109, v108 offset0:28 offset1:29
	v_pk_mul_f32 v[110:111], v[108:109], v[116:117]
	s_nop 0
	v_pk_fma_f32 v[112:113], v[108:109], v[118:119], v[110:111] op_sel:[0,0,1] op_sel_hi:[1,1,0]
	v_pk_fma_f32 v[108:109], v[108:109], v[118:119], v[110:111] op_sel:[0,0,1] op_sel_hi:[1,1,0] neg_lo:[0,0,1] neg_hi:[0,0,1]
	s_nop 0
	v_mov_b32_e32 v113, v109
	s_waitcnt lgkmcnt(2)
	v_mov_b32_e32 v108, v169
	v_mov_b32_e32 v109, v168
	v_pk_add_f32 v[154:155], v[112:113], v[108:109]
	ds_write2st64_b32 v174, v155, v154 offset0:30 offset1:31
	s_cbranch_vccnz .LBB0_272
	v_add_co_u32_e32 v108, vcc, 0x6818000, v106
	s_nop 1
	v_addc_co_u32_e32 v109, vcc, 0, v107, vcc
	v_add_co_u32_e32 v106, vcc, 0x6c18000, v106
	global_store_dword v[108:109], v155, off
	s_nop 0
	v_addc_co_u32_e32 v107, vcc, 0, v107, vcc
	global_store_dword v[106:107], v154, off
	s_branch .LBB0_272
